# grid-barrier polling back-off: s_sleep 1 -> s_sleep 3 in the 28 barrier poll loops (less polling traffic)
# speedup vs baseline: 1.0016x; 1.0016x over previous
.LBB0_14:
	s_sleep 3
	global_load_dword v2, v0, s[2:3] offset:32 sc1
	s_waitcnt vmcnt(0)
	v_and_b32_e32 v2, 0xffff0000, v2
	v_cmp_ne_u32_e32 vcc, v2, v1
	s_or_b64 s[4:5], vcc, s[4:5]
	s_andn2_b64 exec, exec, s[4:5]
	s_cbranch_execnz .LBB0_14

.LBB0_156:
	global_load_dword v15, v16, s[4:5] sc1
	s_waitcnt lgkmcnt(0)
	global_load_dword v0, v16, s[6:7] sc1
	global_load_dword v1, v16, s[8:9] sc1
	global_load_dword v2, v16, s[10:11] sc1
	global_load_dword v3, v16, s[12:13] sc1
	global_load_dword v4, v16, s[14:15] sc1
	global_load_dword v5, v16, s[20:21] sc1
	global_load_dword v6, v16, s[22:23] sc1
	global_load_dword v7, v16, s[24:25] sc1
	global_load_dword v8, v16, s[26:27] sc1
	global_load_dword v9, v16, s[28:29] sc1
	global_load_dword v10, v16, s[30:31] sc1
	global_load_dword v11, v16, s[34:35] sc1
	global_load_dword v12, v16, s[36:37] sc1
	global_load_dword v13, v16, s[38:39] sc1
	global_load_dword v14, v16, s[40:41] sc1
	s_mov_b64 s[42:43], -1
	s_mov_b64 s[44:45], -1
	s_waitcnt vmcnt(14)
	v_add_u32_e32 v17, v0, v15
	s_waitcnt vmcnt(13)
	v_add_u32_e32 v17, v17, v1
	s_waitcnt vmcnt(12)
	v_add_u32_e32 v17, v17, v2
	s_waitcnt vmcnt(11)
	v_add_u32_e32 v17, v17, v3
	s_waitcnt vmcnt(10)
	v_add_u32_e32 v17, v17, v4
	s_waitcnt vmcnt(9)
	v_add_u32_e32 v17, v17, v5
	s_waitcnt vmcnt(8)
	v_add_u32_e32 v17, v17, v6
	s_waitcnt vmcnt(7)
	v_add_u32_e32 v17, v17, v7
	s_waitcnt vmcnt(6)
	v_add_u32_e32 v17, v17, v8
	s_waitcnt vmcnt(5)
	v_add_u32_e32 v17, v17, v9
	s_waitcnt vmcnt(4)
	v_add_u32_e32 v17, v17, v10
	s_waitcnt vmcnt(3)
	v_add_u32_e32 v17, v17, v11
	s_waitcnt vmcnt(2)
	v_add_u32_e32 v17, v17, v12
	s_waitcnt vmcnt(1)
	v_add_u32_e32 v17, v17, v13
	s_waitcnt vmcnt(0)
	v_add_u32_e32 v17, v17, v14
	v_cmp_eq_u32_e32 vcc, s19, v17
	s_cbranch_vccnz .LBB0_155
	s_and_b32 s42, s33, 0xff
	s_cmp_eq_u32 s42, 0
	s_mov_b64 s[42:43], -1
	s_mov_b64 s[46:47], -1
	s_sleep 3
	s_cbranch_scc0 .LBB0_160
	global_load_dword v17, v16, s[2:3] sc1
	s_waitcnt vmcnt(0)
	v_cmp_eq_u32_e32 vcc, 0, v17
	s_cbranch_vccnz .LBB0_162
	s_mov_b64 s[46:47], 0

.LBB0_174:
	s_and_b32 s22, s19, 0xff
	s_mov_b64 s[20:21], -1
	s_cmp_lg_u32 s22, 0
	s_mov_b64 s[24:25], -1
	s_sleep 3
	s_cbranch_scc1 .LBB0_177
	global_load_dword v2, v0, s[8:9] sc1
	s_waitcnt vmcnt(0)
	v_cmp_eq_u32_e32 vcc, 0, v2
	s_cbranch_vccnz .LBB0_179
	s_mov_b64 s[24:25], 0
	s_mov_b64 s[22:23], -1

.LBB0_191:
	s_and_b32 s20, s19, 0xff
	s_cmp_lg_u32 s20, 0
	s_mov_b64 s[22:23], -1
	s_sleep 3
	s_cbranch_scc1 .LBB0_194
	global_load_dword v1, v0, s[8:9] sc1
	s_waitcnt vmcnt(0)
	v_cmp_eq_u32_e32 vcc, 0, v1
	s_cbranch_vccnz .LBB0_196
	s_mov_b64 s[22:23], 0
	s_mov_b64 s[20:21], -1

.LBB0_637:
	global_load_dword v15, v16, s[4:5] sc1
	s_waitcnt lgkmcnt(0)
	global_load_dword v0, v16, s[6:7] sc1
	global_load_dword v1, v16, s[8:9] sc1
	global_load_dword v2, v16, s[10:11] sc1
	global_load_dword v3, v16, s[12:13] sc1
	global_load_dword v4, v16, s[14:15] sc1
	global_load_dword v5, v16, s[16:17] sc1
	global_load_dword v6, v16, s[18:19] sc1
	global_load_dword v7, v16, s[20:21] sc1
	global_load_dword v8, v16, s[22:23] sc1
	global_load_dword v9, v16, s[24:25] sc1
	global_load_dword v10, v16, s[26:27] sc1
	global_load_dword v11, v16, s[28:29] sc1
	global_load_dword v12, v16, s[30:31] sc1
	global_load_dword v13, v16, s[34:35] sc1
	global_load_dword v14, v16, s[36:37] sc1
	s_mov_b64 s[38:39], -1
	s_mov_b64 s[40:41], -1
	s_waitcnt vmcnt(14)
	v_add_u32_e32 v17, v0, v15
	s_waitcnt vmcnt(13)
	v_add_u32_e32 v17, v17, v1
	s_waitcnt vmcnt(12)
	v_add_u32_e32 v17, v17, v2
	s_waitcnt vmcnt(11)
	v_add_u32_e32 v17, v17, v3
	s_waitcnt vmcnt(10)
	v_add_u32_e32 v17, v17, v4
	s_waitcnt vmcnt(9)
	v_add_u32_e32 v17, v17, v5
	s_waitcnt vmcnt(8)
	v_add_u32_e32 v17, v17, v6
	s_waitcnt vmcnt(7)
	v_add_u32_e32 v17, v17, v7
	s_waitcnt vmcnt(6)
	v_add_u32_e32 v17, v17, v8
	s_waitcnt vmcnt(5)
	v_add_u32_e32 v17, v17, v9
	s_waitcnt vmcnt(4)
	v_add_u32_e32 v17, v17, v10
	s_waitcnt vmcnt(3)
	v_add_u32_e32 v17, v17, v11
	s_waitcnt vmcnt(2)
	v_add_u32_e32 v17, v17, v12
	s_waitcnt vmcnt(1)
	v_add_u32_e32 v17, v17, v13
	s_waitcnt vmcnt(0)
	v_add_u32_e32 v17, v17, v14
	v_cmp_eq_u32_e32 vcc, s33, v17
	s_cbranch_vccnz .LBB0_636
	s_and_b32 s38, s44, 0xff
	s_cmp_eq_u32 s38, 0
	s_mov_b64 s[38:39], -1
	s_mov_b64 s[42:43], -1
	s_sleep 3
	s_cbranch_scc0 .LBB0_641
	global_load_dword v17, v16, s[2:3] sc1
	s_waitcnt vmcnt(0)
	v_cmp_eq_u32_e32 vcc, 0, v17
	s_cbranch_vccnz .LBB0_643
	s_mov_b64 s[42:43], 0

.LBB0_655:
	s_and_b32 s18, s22, 0xff
	s_mov_b64 s[16:17], -1
	s_cmp_lg_u32 s18, 0
	s_mov_b64 s[20:21], -1
	s_sleep 3
	s_cbranch_scc1 .LBB0_658
	global_load_dword v2, v0, s[8:9] sc1
	s_waitcnt vmcnt(0)
	v_cmp_eq_u32_e32 vcc, 0, v2
	s_cbranch_vccnz .LBB0_660
	s_mov_b64 s[20:21], 0
	s_mov_b64 s[18:19], -1

.LBB0_672:
	s_and_b32 s16, s22, 0xff
	s_cmp_lg_u32 s16, 0
	s_mov_b64 s[18:19], -1
	s_sleep 3
	s_cbranch_scc1 .LBB0_675
	global_load_dword v1, v0, s[8:9] sc1
	s_waitcnt vmcnt(0)
	v_cmp_eq_u32_e32 vcc, 0, v1
	s_cbranch_vccnz .LBB0_677
	s_mov_b64 s[18:19], 0
	s_mov_b64 s[16:17], -1

.LBB0_825:
	global_load_dword v15, v16, s[6:7] sc1
	s_waitcnt lgkmcnt(0)
	global_load_dword v0, v16, s[8:9] sc1
	global_load_dword v1, v16, s[10:11] sc1
	global_load_dword v2, v16, s[12:13] sc1
	global_load_dword v3, v16, s[14:15] sc1
	global_load_dword v4, v16, s[16:17] sc1
	global_load_dword v5, v16, s[18:19] sc1
	global_load_dword v6, v16, s[20:21] sc1
	global_load_dword v7, v16, s[22:23] sc1
	global_load_dword v8, v16, s[24:25] sc1
	global_load_dword v9, v16, s[26:27] sc1
	global_load_dword v10, v16, s[28:29] sc1
	global_load_dword v11, v16, s[30:31] sc1
	global_load_dword v12, v16, s[34:35] sc1
	global_load_dword v13, v16, s[36:37] sc1
	global_load_dword v14, v16, s[38:39] sc1
	s_mov_b64 s[40:41], -1
	s_mov_b64 s[42:43], -1
	s_waitcnt vmcnt(14)
	v_add_u32_e32 v17, v0, v15
	s_waitcnt vmcnt(13)
	v_add_u32_e32 v17, v17, v1
	s_waitcnt vmcnt(12)
	v_add_u32_e32 v17, v17, v2
	s_waitcnt vmcnt(11)
	v_add_u32_e32 v17, v17, v3
	s_waitcnt vmcnt(10)
	v_add_u32_e32 v17, v17, v4
	s_waitcnt vmcnt(9)
	v_add_u32_e32 v17, v17, v5
	s_waitcnt vmcnt(8)
	v_add_u32_e32 v17, v17, v6
	s_waitcnt vmcnt(7)
	v_add_u32_e32 v17, v17, v7
	s_waitcnt vmcnt(6)
	v_add_u32_e32 v17, v17, v8
	s_waitcnt vmcnt(5)
	v_add_u32_e32 v17, v17, v9
	s_waitcnt vmcnt(4)
	v_add_u32_e32 v17, v17, v10
	s_waitcnt vmcnt(3)
	v_add_u32_e32 v17, v17, v11
	s_waitcnt vmcnt(2)
	v_add_u32_e32 v17, v17, v12
	s_waitcnt vmcnt(1)
	v_add_u32_e32 v17, v17, v13
	s_waitcnt vmcnt(0)
	v_add_u32_e32 v17, v17, v14
	v_cmp_eq_u32_e32 vcc, s33, v17
	s_cbranch_vccnz .LBB0_824
	s_and_b32 s40, s46, 0xff
	s_cmp_eq_u32 s40, 0
	s_mov_b64 s[40:41], -1
	s_mov_b64 s[44:45], -1
	s_sleep 3
	s_cbranch_scc0 .LBB0_829
	global_load_dword v17, v16, s[2:3] sc1
	s_waitcnt vmcnt(0)
	v_cmp_eq_u32_e32 vcc, 0, v17
	s_cbranch_vccnz .LBB0_831
	s_mov_b64 s[44:45], 0

.LBB0_843:
	s_and_b32 s20, s24, 0xff
	s_mov_b64 s[18:19], -1
	s_cmp_lg_u32 s20, 0
	s_mov_b64 s[22:23], -1
	s_sleep 3
	s_cbranch_scc1 .LBB0_846
	global_load_dword v2, v0, s[10:11] sc1
	s_waitcnt vmcnt(0)
	v_cmp_eq_u32_e32 vcc, 0, v2
	s_cbranch_vccnz .LBB0_848
	s_mov_b64 s[22:23], 0
	s_mov_b64 s[20:21], -1

.LBB0_860:
	s_and_b32 s18, s24, 0xff
	s_cmp_lg_u32 s18, 0
	s_mov_b64 s[20:21], -1
	s_sleep 3
	s_cbranch_scc1 .LBB0_863
	global_load_dword v1, v0, s[10:11] sc1
	s_waitcnt vmcnt(0)
	v_cmp_eq_u32_e32 vcc, 0, v1
	s_cbranch_vccnz .LBB0_865
	s_mov_b64 s[20:21], 0
	s_mov_b64 s[18:19], -1

.LBB0_992:
	global_load_dword v15, v16, s[4:5] sc1
	s_waitcnt lgkmcnt(0)
	global_load_dword v0, v16, s[8:9] sc1
	global_load_dword v1, v16, s[10:11] sc1
	global_load_dword v2, v16, s[12:13] sc1
	global_load_dword v3, v16, s[14:15] sc1
	global_load_dword v4, v16, s[16:17] sc1
	global_load_dword v5, v16, s[18:19] sc1
	global_load_dword v6, v16, s[20:21] sc1
	global_load_dword v7, v16, s[22:23] sc1
	global_load_dword v8, v16, s[24:25] sc1
	global_load_dword v9, v16, s[26:27] sc1
	global_load_dword v10, v16, s[28:29] sc1
	global_load_dword v11, v16, s[30:31] sc1
	global_load_dword v12, v16, s[34:35] sc1
	global_load_dword v13, v16, s[36:37] sc1
	global_load_dword v14, v16, s[38:39] sc1
	s_mov_b64 s[40:41], -1
	s_mov_b64 s[42:43], -1
	s_waitcnt vmcnt(14)
	v_add_u32_e32 v17, v0, v15
	s_waitcnt vmcnt(13)
	v_add_u32_e32 v17, v17, v1
	s_waitcnt vmcnt(12)
	v_add_u32_e32 v17, v17, v2
	s_waitcnt vmcnt(11)
	v_add_u32_e32 v17, v17, v3
	s_waitcnt vmcnt(10)
	v_add_u32_e32 v17, v17, v4
	s_waitcnt vmcnt(9)
	v_add_u32_e32 v17, v17, v5
	s_waitcnt vmcnt(8)
	v_add_u32_e32 v17, v17, v6
	s_waitcnt vmcnt(7)
	v_add_u32_e32 v17, v17, v7
	s_waitcnt vmcnt(6)
	v_add_u32_e32 v17, v17, v8
	s_waitcnt vmcnt(5)
	v_add_u32_e32 v17, v17, v9
	s_waitcnt vmcnt(4)
	v_add_u32_e32 v17, v17, v10
	s_waitcnt vmcnt(3)
	v_add_u32_e32 v17, v17, v11
	s_waitcnt vmcnt(2)
	v_add_u32_e32 v17, v17, v12
	s_waitcnt vmcnt(1)
	v_add_u32_e32 v17, v17, v13
	s_waitcnt vmcnt(0)
	v_add_u32_e32 v17, v17, v14
	v_cmp_eq_u32_e32 vcc, s33, v17
	s_cbranch_vccnz .LBB0_991
	s_and_b32 s40, s46, 0xff
	s_cmp_eq_u32 s40, 0
	s_mov_b64 s[40:41], -1
	s_mov_b64 s[44:45], -1
	s_sleep 3
	s_cbranch_scc0 .LBB0_996
	global_load_dword v17, v16, s[2:3] sc1
	s_waitcnt vmcnt(0)
	v_cmp_eq_u32_e32 vcc, 0, v17
	s_cbranch_vccnz .LBB0_998
	s_mov_b64 s[44:45], 0
